# m4_attn_pipe_balanced_exps
# speedup vs baseline: 1.0266x; 1.0116x over previous
.LBB0_192:
	v_mfma_f32_32x32x16_bf16 v[50:65], v[130:133], v[82:85], v[50:65]
	ds_read_b128 v[182:185], v169 offset:24576
	ds_read_b128 v[198:201], v170 offset:24576
	ds_read_b128 v[202:205], v171 offset:24576
	v_exp_f32_e32 v149, v66
	s_or_b32 s0, s0, 32
	s_cmp_lt_u32 s0, s84
	s_cselect_b64 s[42:43], -1, 0
	s_cmp_lg_u32 s0, s84
	v_mfma_f32_32x32x16_bf16 v[34:49], v[126:129], v[82:85], v[34:49]
	ds_read_b128 v[206:209], v172 offset:24576
	ds_read_b64_tr_b16 v[130:131], v173 offset:16384
	ds_read_b64_tr_b16 v[132:133], v174 offset:16384
	v_exp_f32_e32 v150, v67
	v_mfma_f32_32x32x16_bf16 v[18:33], v[122:125], v[82:85], v[18:33]
	ds_read_b64_tr_b16 v[126:127], v175 offset:16384
	ds_read_b64_tr_b16 v[128:129], v176 offset:16384
	ds_read_b64_tr_b16 v[122:123], v177 offset:16384
	v_exp_f32_e32 v151, v68
	v_mfma_f32_32x32x16_bf16 v[2:17], v[118:121], v[82:85], v[2:17]
	ds_read_b64_tr_b16 v[124:125], v178 offset:16384
	ds_read_b64_tr_b16 v[118:119], v179 offset:16384
	ds_read_b64_tr_b16 v[120:121], v180 offset:16384
	v_exp_f32_e32 v152, v69
	v_lshl_add_u64 v[250:251], v[248:249], 0, s[46:47]
	s_mov_b32 m0, s101
	s_nop 0
	global_load_lds_dwordx4 v[250:251], off
	v_or_b32_e32 v82, s0, v166
	v_sub_u32_e32 v82, v167, v82
	v_cvt_f32_i32_e32 v83, v82
	v_fma_f32 v96, -v158, |v83|, v146
	v_mfma_f32_32x32x16_bf16 v[50:65], v[114:117], v[86:89], v[50:65]
	ds_read_b64_tr_b16 v[114:115], v173 offset:20480
	ds_read_b64_tr_b16 v[116:117], v174 offset:20480
	v_exp_f32_e32 v153, v70
	v_mfma_f32_32x32x16_bf16 v[34:49], v[134:137], v[86:89], v[34:49]
	ds_read_b64_tr_b16 v[134:135], v175 offset:20480
	ds_read_b64_tr_b16 v[136:137], v176 offset:20480
	v_exp_f32_e32 v164, v71
	v_mfma_f32_32x32x16_bf16 v[18:33], v[138:141], v[86:89], v[18:33]
	ds_read_b64_tr_b16 v[138:139], v177 offset:20480
	ds_read_b64_tr_b16 v[140:141], v178 offset:20480
	v_exp_f32_e32 v181, v72
	v_mfma_f32_32x32x16_bf16 v[2:17], v[142:145], v[86:89], v[2:17]
	ds_read_b64_tr_b16 v[142:143], v179 offset:20480
	ds_read_b64_tr_b16 v[144:145], v180 offset:20480
	v_exp_f32_e32 v225, v73
	s_cbranch_scc1 .LBB0_194
	v_add_u32_e32 v83, -2, v82
	v_cvt_f32_i32_e32 v83, v83
	v_add_u32_e32 v84, -1, v82
	v_cvt_f32_i32_e32 v84, v84
	v_add_u32_e32 v86, -8, v82
	v_and_b32_e32 v85, 0x7fffffff, v83
	v_add_u32_e32 v83, -3, v82
	v_cvt_f32_i32_e32 v83, v83
	v_cvt_f32_i32_e32 v86, v86
	v_and_b32_e32 v84, 0x7fffffff, v84
	v_pk_fma_f32 v[210:211], v[162:163], v[84:85], v[146:147] op_sel_hi:[1,1,0]
	v_and_b32_e32 v84, 0x7fffffff, v83
	v_add_u32_e32 v83, -10, v82
	v_cvt_f32_i32_e32 v83, v83
	v_and_b32_e32 v85, 0x7fffffff, v86
	v_pk_fma_f32 v[212:213], v[162:163], v[84:85], v[146:147] op_sel_hi:[1,1,0]
	v_add_u32_e32 v84, -9, v82
	v_cvt_f32_i32_e32 v84, v84
	v_and_b32_e32 v85, 0x7fffffff, v83
	v_add_u32_e32 v83, -16, v82
	v_cvt_f32_i32_e32 v83, v83
	v_add_u32_e32 v86, -11, v82
	v_cvt_f32_i32_e32 v86, v86
	v_and_b32_e32 v84, 0x7fffffff, v84
	v_pk_fma_f32 v[214:215], v[162:163], v[84:85], v[146:147] op_sel_hi:[1,1,0]
	v_and_b32_e32 v85, 0x7fffffff, v83
	v_subrev_u32_e32 v83, 18, v82
	v_cvt_f32_i32_e32 v83, v83
	v_and_b32_e32 v84, 0x7fffffff, v86
	v_pk_fma_f32 v[216:217], v[162:163], v[84:85], v[146:147] op_sel_hi:[1,1,0]
	v_subrev_u32_e32 v84, 17, v82
	v_cvt_f32_i32_e32 v84, v84
	v_and_b32_e32 v85, 0x7fffffff, v83
	v_subrev_u32_e32 v83, 24, v82
	v_subrev_u32_e32 v86, 19, v82
	v_cvt_f32_i32_e32 v83, v83
	v_cvt_f32_i32_e32 v86, v86
	v_and_b32_e32 v84, 0x7fffffff, v84
	v_pk_fma_f32 v[218:219], v[162:163], v[84:85], v[146:147] op_sel_hi:[1,1,0]
	v_and_b32_e32 v85, 0x7fffffff, v83
	v_and_b32_e32 v84, 0x7fffffff, v86
	v_pk_fma_f32 v[220:221], v[162:163], v[84:85], v[146:147] op_sel_hi:[1,1,0]
	v_subrev_u32_e32 v83, 26, v82
	v_subrev_u32_e32 v84, 25, v82
	v_cvt_f32_i32_e32 v83, v83
	v_cvt_f32_i32_e32 v84, v84
	v_subrev_u32_e32 v82, 27, v82
	v_cvt_f32_i32_e32 v85, v82
	v_and_b32_e32 v83, 0x7fffffff, v83
	v_and_b32_e32 v82, 0x7fffffff, v84
	v_mov_b32_e32 v97, v210
	v_pk_fma_f32 v[222:223], v[162:163], v[82:83], v[146:147] op_sel_hi:[1,1,0]
	v_fma_f32 v224, -v158, |v85|, v146
	v_mov_b64_e32 v[82:83], v[96:97]
	v_mov_b64_e32 v[84:85], v[98:99]
	v_mov_b64_e32 v[86:87], v[100:101]
	v_mov_b64_e32 v[88:89], v[102:103]
	v_mov_b64_e32 v[90:91], v[104:105]
	v_mov_b64_e32 v[92:93], v[106:107]
	v_mov_b64_e32 v[94:95], v[108:109]
	v_mov_b64_e32 v[96:97], v[110:111]
	v_mov_b32_e32 v84, v211
	v_mov_b32_e32 v85, v212
	v_mov_b32_e32 v86, v213
	v_mov_b32_e32 v87, v214
	v_mov_b32_e32 v88, v215
	v_mov_b32_e32 v89, v216
	v_mov_b32_e32 v90, v217
	v_mov_b32_e32 v91, v218
	v_mov_b32_e32 v92, v219
	v_mov_b32_e32 v93, v220
	v_mov_b32_e32 v94, v221
	v_mov_b32_e32 v95, v222
	v_mov_b32_e32 v96, v223
	v_mov_b32_e32 v97, v224
	s_branch .LBB0_195

.LBB0_197:
	v_add_f32_e32 v147, v148, v147
	s_waitcnt lgkmcnt(0)
	v_mfma_f32_32x32x16_bf16 v[82:97], v[182:185], v[98:101], v[82:97]
	v_exp_f32_e32 v183, v74
	v_exp_f32_e32 v184, v75
	v_add_f32_e32 v148, 0, v149
	v_add_f32_e32 v148, v150, v148
	v_exp_f32_e32 v185, v76
	v_mfma_f32_32x32x16_bf16 v[82:97], v[198:201], v[102:105], v[82:97]
	v_exp_f32_e32 v198, v77
	v_add_f32_e32 v148, v151, v148
	v_add_f32_e32 v148, v152, v148
	v_exp_f32_e32 v199, v78
	v_add_f32_e32 v148, v153, v148
	v_mfma_f32_32x32x16_bf16 v[82:97], v[202:205], v[106:109], v[82:97]
	v_exp_f32_e32 v200, v79
	v_add_f32_e32 v148, v164, v148
	v_add_f32_e32 v148, v181, v148
	v_exp_f32_e32 v201, v80
	v_add_f32_e32 v148, v225, v148
	v_mfma_f32_32x32x16_bf16 v[82:97], v[206:209], v[110:113], v[82:97]
	v_exp_f32_e32 v202, v81
	v_add_f32_e32 v148, v183, v148
	v_add_f32_e32 v148, v184, v148
	v_add_f32_e32 v148, v185, v148
	v_add_f32_e32 v148, v198, v148
	v_add_f32_e32 v148, v199, v148
	v_add_f32_e32 v148, v200, v148
	v_add_f32_e32 v148, v201, v148
	v_add_f32_e32 v148, v202, v148
	v_cmp_nge_f32_e32 vcc, s12, v148
	s_cbranch_vccz .LBB0_199
	v_max_f32_e32 v146, v67, v67
	v_max_f32_e32 v148, v66, v66
	v_max_f32_e32 v146, v148, v146
	v_max3_f32 v146, v146, v68, v69
	v_max3_f32 v146, v146, v70, v71
	v_max3_f32 v146, v146, v72, v73
	v_max3_f32 v146, v146, v74, v75
	v_max3_f32 v146, v146, v76, v77
	v_max3_f32 v146, v146, v78, v79
	v_max3_f32 v146, v146, v80, v81
	ds_bpermute_b32 v148, v159, v146
	s_waitcnt lgkmcnt(0)
	v_max3_f32 v148, v146, v148, 0
	v_sub_f32_e32 v66, v66, v148
	v_exp_f32_e32 v66, v66
	v_sub_f32_e32 v67, v67, v148
	v_exp_f32_e32 v67, v67
	v_sub_f32_e32 v68, v68, v148
	v_exp_f32_e32 v68, v68
	v_sub_f32_e32 v69, v69, v148
	v_exp_f32_e32 v69, v69
	v_sub_f32_e32 v70, v70, v148
	v_sub_f32_e32 v71, v71, v148
	v_add_f32_e32 v149, 0, v66
	v_exp_f32_e32 v70, v70
	v_exp_f32_e32 v71, v71
	v_add_f32_e32 v149, v67, v149
	v_sub_f32_e32 v72, v72, v148
	v_sub_f32_e32 v73, v73, v148
	v_add_f32_e32 v149, v68, v149
	v_exp_f32_e32 v72, v72
	v_exp_f32_e32 v73, v73
	v_add_f32_e32 v149, v69, v149
	v_add_f32_e32 v149, v70, v149
	v_cvt_pk_bf16_f32 v66, v66, v67
	v_cvt_pk_bf16_f32 v67, v68, v69
	v_cvt_pk_bf16_f32 v68, v70, v71
	v_sub_f32_e32 v70, v74, v148
	v_add_f32_e32 v149, v71, v149
	v_exp_f32_e32 v70, v70
	v_sub_f32_e32 v71, v75, v148
	v_add_f32_e32 v149, v72, v149
	v_cvt_pk_bf16_f32 v69, v72, v73
	v_exp_f32_e32 v71, v71
	v_sub_f32_e32 v72, v76, v148
	v_add_f32_e32 v149, v73, v149
	v_exp_f32_e32 v72, v72
	v_sub_f32_e32 v73, v77, v148
	v_exp_f32_e32 v73, v73
	v_sub_f32_e32 v75, v78, v148
	v_add_f32_e32 v74, v70, v149
	v_exp_f32_e32 v75, v75
	v_sub_f32_e32 v76, v79, v148
	v_add_f32_e32 v74, v71, v74
	v_exp_f32_e32 v76, v76
	v_sub_f32_e32 v77, v80, v148
	v_add_f32_e32 v74, v72, v74
	v_exp_f32_e32 v77, v77
	v_sub_f32_e32 v78, v81, v148
	v_exp_f32_e64 v146, -v148
	v_add_f32_e32 v74, v73, v74
	v_exp_f32_e32 v78, v78
	v_add_f32_e32 v74, v75, v74
	v_add_f32_e32 v74, v76, v74
	v_add_f32_e32 v0, v0, v148
	v_add_f32_e32 v74, v77, v74
	v_pk_mul_f32 v[64:65], v[64:65], v[146:147] op_sel_hi:[1,0]
	v_pk_mul_f32 v[62:63], v[62:63], v[146:147] op_sel_hi:[1,0]
	v_pk_mul_f32 v[60:61], v[60:61], v[146:147] op_sel_hi:[1,0]
	v_pk_mul_f32 v[58:59], v[58:59], v[146:147] op_sel_hi:[1,0]
	v_pk_mul_f32 v[56:57], v[56:57], v[146:147] op_sel_hi:[1,0]
	v_pk_mul_f32 v[54:55], v[54:55], v[146:147] op_sel_hi:[1,0]
	v_pk_mul_f32 v[52:53], v[52:53], v[146:147] op_sel_hi:[1,0]
	v_pk_mul_f32 v[50:51], v[50:51], v[146:147] op_sel_hi:[1,0]
	v_pk_mul_f32 v[48:49], v[48:49], v[146:147] op_sel_hi:[1,0]
	v_pk_mul_f32 v[46:47], v[46:47], v[146:147] op_sel_hi:[1,0]
	v_pk_mul_f32 v[44:45], v[44:45], v[146:147] op_sel_hi:[1,0]
	v_pk_mul_f32 v[42:43], v[42:43], v[146:147] op_sel_hi:[1,0]
	v_pk_mul_f32 v[40:41], v[40:41], v[146:147] op_sel_hi:[1,0]
	v_pk_mul_f32 v[38:39], v[38:39], v[146:147] op_sel_hi:[1,0]
	v_pk_mul_f32 v[36:37], v[36:37], v[146:147] op_sel_hi:[1,0]
	v_pk_mul_f32 v[34:35], v[34:35], v[146:147] op_sel_hi:[1,0]
	v_pk_mul_f32 v[32:33], v[32:33], v[146:147] op_sel_hi:[1,0]
	v_pk_mul_f32 v[30:31], v[30:31], v[146:147] op_sel_hi:[1,0]
	v_pk_mul_f32 v[28:29], v[28:29], v[146:147] op_sel_hi:[1,0]
	v_pk_mul_f32 v[26:27], v[26:27], v[146:147] op_sel_hi:[1,0]
	v_pk_mul_f32 v[24:25], v[24:25], v[146:147] op_sel_hi:[1,0]
	v_pk_mul_f32 v[22:23], v[22:23], v[146:147] op_sel_hi:[1,0]
	v_pk_mul_f32 v[20:21], v[20:21], v[146:147] op_sel_hi:[1,0]
	v_pk_mul_f32 v[18:19], v[18:19], v[146:147] op_sel_hi:[1,0]
	v_pk_mul_f32 v[16:17], v[16:17], v[146:147] op_sel_hi:[1,0]
	v_pk_mul_f32 v[14:15], v[14:15], v[146:147] op_sel_hi:[1,0]
	v_pk_mul_f32 v[12:13], v[12:13], v[146:147] op_sel_hi:[1,0]
	v_pk_mul_f32 v[10:11], v[10:11], v[146:147] op_sel_hi:[1,0]
	v_pk_mul_f32 v[8:9], v[8:9], v[146:147] op_sel_hi:[1,0]
	v_pk_mul_f32 v[6:7], v[6:7], v[146:147] op_sel_hi:[1,0]
	v_pk_mul_f32 v[4:5], v[4:5], v[146:147] op_sel_hi:[1,0]
	v_pk_mul_f32 v[2:3], v[2:3], v[146:147] op_sel_hi:[1,0]
	v_sub_f32_e32 v97, v97, v148
	v_sub_f32_e32 v96, v96, v148
	v_sub_f32_e32 v95, v95, v148
	v_sub_f32_e32 v94, v94, v148
	v_sub_f32_e32 v93, v93, v148
	v_sub_f32_e32 v92, v92, v148
	v_sub_f32_e32 v91, v91, v148
	v_sub_f32_e32 v90, v90, v148
	v_sub_f32_e32 v89, v89, v148
	v_sub_f32_e32 v88, v88, v148
	v_sub_f32_e32 v87, v87, v148
	v_sub_f32_e32 v86, v86, v148
	v_sub_f32_e32 v85, v85, v148
	v_sub_f32_e32 v84, v84, v148
	v_sub_f32_e32 v83, v83, v148
	v_sub_f32_e32 v82, v82, v148
	v_add_f32_e32 v148, v78, v74
	v_cvt_pk_bf16_f32 v70, v70, v71
	v_cvt_pk_bf16_f32 v71, v72, v73
	v_cvt_pk_bf16_f32 v72, v75, v76
	v_cvt_pk_bf16_f32 v73, v77, v78
	v_mul_f32_e32 v147, v147, v146
	v_xor_b32_e32 v146, 0x80000000, v0
	s_branch .LBB0_200
.LBB0_199:
	v_cvt_pk_bf16_f32 v66, v149, v150
	v_cvt_pk_bf16_f32 v67, v151, v152
	v_cvt_pk_bf16_f32 v68, v153, v164
	v_cvt_pk_bf16_f32 v69, v181, v225
	v_cvt_pk_bf16_f32 v70, v183, v184
	v_cvt_pk_bf16_f32 v71, v185, v198
	v_cvt_pk_bf16_f32 v72, v199, v200
	v_cvt_pk_bf16_f32 v73, v201, v202
.LBB0_200:
	v_mfma_f32_32x32x16_bf16 v[50:65], v[130:133], v[66:69], v[50:65]
	ds_read_b128 v[182:185], v169 offset:32768
	ds_read_b128 v[198:201], v170 offset:32768
	ds_read_b128 v[202:205], v171 offset:32768
	v_exp_f32_e32 v149, v82
	s_add_i32 s0, s97, 0xffffff00
	s_and_b32 s0, s0, 0xf80
	s_cmp_lt_u32 s0, s84
	s_cselect_b64 s[44:45], -1, 0
	s_cmp_lg_u32 s0, s84
	v_mfma_f32_32x32x16_bf16 v[34:49], v[126:129], v[66:69], v[34:49]
	ds_read_b128 v[206:209], v172 offset:32768
	ds_read_b64_tr_b16 v[130:131], v173 offset:24576
	ds_read_b64_tr_b16 v[132:133], v174 offset:24576
	v_exp_f32_e32 v150, v83
	v_mfma_f32_32x32x16_bf16 v[18:33], v[122:125], v[66:69], v[18:33]
	ds_read_b64_tr_b16 v[126:127], v175 offset:24576
	ds_read_b64_tr_b16 v[128:129], v176 offset:24576
	ds_read_b64_tr_b16 v[122:123], v177 offset:24576
	v_exp_f32_e32 v151, v84
	v_mfma_f32_32x32x16_bf16 v[2:17], v[118:121], v[66:69], v[2:17]
	ds_read_b64_tr_b16 v[124:125], v178 offset:24576
	ds_read_b64_tr_b16 v[118:119], v179 offset:24576
	ds_read_b64_tr_b16 v[120:121], v180 offset:24576
	v_exp_f32_e32 v152, v85
	v_lshl_add_u64 v[250:251], v[248:249], 0, s[56:57]
	s_mov_b32 m0, s87
	s_nop 0
	global_load_lds_dwordx4 v[250:251], off
	v_or_b32_e32 v66, s0, v166
	v_sub_u32_e32 v66, v167, v66
	v_cvt_f32_i32_e32 v67, v66
	v_fma_f32 v80, -v158, |v67|, v146
	v_mfma_f32_32x32x16_bf16 v[50:65], v[114:117], v[70:73], v[50:65]
	ds_read_b64_tr_b16 v[114:115], v173 offset:28672
	ds_read_b64_tr_b16 v[116:117], v174 offset:28672
	v_exp_f32_e32 v153, v86
	v_mfma_f32_32x32x16_bf16 v[34:49], v[134:137], v[70:73], v[34:49]
	ds_read_b64_tr_b16 v[134:135], v175 offset:28672
	ds_read_b64_tr_b16 v[136:137], v176 offset:28672
	v_exp_f32_e32 v164, v87
	v_mfma_f32_32x32x16_bf16 v[18:33], v[138:141], v[70:73], v[18:33]
	ds_read_b64_tr_b16 v[138:139], v177 offset:28672
	ds_read_b64_tr_b16 v[140:141], v178 offset:28672
	v_exp_f32_e32 v181, v88
	v_mfma_f32_32x32x16_bf16 v[2:17], v[142:145], v[70:73], v[2:17]
	ds_read_b64_tr_b16 v[142:143], v179 offset:28672
	ds_read_b64_tr_b16 v[144:145], v180 offset:28672
	v_exp_f32_e32 v225, v89
	s_cbranch_scc1 .LBB0_202
	v_add_u32_e32 v67, -2, v66
	v_cvt_f32_i32_e32 v67, v67
	v_add_u32_e32 v68, -1, v66
	v_cvt_f32_i32_e32 v68, v68
	v_add_u32_e32 v70, -8, v66
	v_and_b32_e32 v69, 0x7fffffff, v67
	v_add_u32_e32 v67, -3, v66
	v_cvt_f32_i32_e32 v67, v67
	v_cvt_f32_i32_e32 v70, v70
	v_and_b32_e32 v68, 0x7fffffff, v68
	v_pk_fma_f32 v[210:211], v[162:163], v[68:69], v[146:147] op_sel_hi:[1,1,0]
	v_and_b32_e32 v68, 0x7fffffff, v67
	v_add_u32_e32 v67, -10, v66
	v_cvt_f32_i32_e32 v67, v67
	v_and_b32_e32 v69, 0x7fffffff, v70
	v_pk_fma_f32 v[212:213], v[162:163], v[68:69], v[146:147] op_sel_hi:[1,1,0]
	v_add_u32_e32 v68, -9, v66
	v_cvt_f32_i32_e32 v68, v68
	v_and_b32_e32 v69, 0x7fffffff, v67
	v_add_u32_e32 v67, -16, v66
	v_cvt_f32_i32_e32 v67, v67
	v_add_u32_e32 v70, -11, v66
	v_cvt_f32_i32_e32 v70, v70
	v_and_b32_e32 v68, 0x7fffffff, v68
	v_pk_fma_f32 v[214:215], v[162:163], v[68:69], v[146:147] op_sel_hi:[1,1,0]
	v_and_b32_e32 v69, 0x7fffffff, v67
	v_subrev_u32_e32 v67, 18, v66
	v_cvt_f32_i32_e32 v67, v67
	v_and_b32_e32 v68, 0x7fffffff, v70
	v_pk_fma_f32 v[216:217], v[162:163], v[68:69], v[146:147] op_sel_hi:[1,1,0]
	v_subrev_u32_e32 v68, 17, v66
	v_cvt_f32_i32_e32 v68, v68
	v_and_b32_e32 v69, 0x7fffffff, v67
	v_subrev_u32_e32 v67, 24, v66
	v_subrev_u32_e32 v70, 19, v66
	v_cvt_f32_i32_e32 v67, v67
	v_cvt_f32_i32_e32 v70, v70
	v_and_b32_e32 v68, 0x7fffffff, v68
	v_pk_fma_f32 v[218:219], v[162:163], v[68:69], v[146:147] op_sel_hi:[1,1,0]
	v_and_b32_e32 v69, 0x7fffffff, v67
	v_and_b32_e32 v68, 0x7fffffff, v70
	v_pk_fma_f32 v[220:221], v[162:163], v[68:69], v[146:147] op_sel_hi:[1,1,0]
	v_subrev_u32_e32 v67, 26, v66
	v_subrev_u32_e32 v68, 25, v66
	v_cvt_f32_i32_e32 v67, v67
	v_cvt_f32_i32_e32 v68, v68
	v_subrev_u32_e32 v66, 27, v66
	v_cvt_f32_i32_e32 v69, v66
	v_and_b32_e32 v67, 0x7fffffff, v67
	v_and_b32_e32 v66, 0x7fffffff, v68
	v_mov_b32_e32 v81, v210
	v_pk_fma_f32 v[222:223], v[162:163], v[66:67], v[146:147] op_sel_hi:[1,1,0]
	v_fma_f32 v224, -v158, |v69|, v146
	v_mov_b64_e32 v[66:67], v[80:81]
	v_mov_b64_e32 v[68:69], v[82:83]
	v_mov_b64_e32 v[70:71], v[84:85]
	v_mov_b64_e32 v[72:73], v[86:87]
	v_mov_b64_e32 v[74:75], v[88:89]
	v_mov_b64_e32 v[76:77], v[90:91]
	v_mov_b64_e32 v[78:79], v[92:93]
	v_mov_b64_e32 v[80:81], v[94:95]
	v_mov_b32_e32 v68, v211
	v_mov_b32_e32 v69, v212
	v_mov_b32_e32 v70, v213
	v_mov_b32_e32 v71, v214
	v_mov_b32_e32 v72, v215
	v_mov_b32_e32 v73, v216
	v_mov_b32_e32 v74, v217
	v_mov_b32_e32 v75, v218
	v_mov_b32_e32 v76, v219
	v_mov_b32_e32 v77, v220
	v_mov_b32_e32 v78, v221
	v_mov_b32_e32 v79, v222
	v_mov_b32_e32 v80, v223
	v_mov_b32_e32 v81, v224
	s_branch .LBB0_203

.LBB0_203:
	v_lshl_add_u64 v[250:251], v[248:249], 0, s[68:69]
	s_mov_b32 m0, s86
	s_nop 0
	global_load_lds_dwordx4 v[250:251], off
	v_add_f32_e32 v147, v148, v147
	s_waitcnt lgkmcnt(0)
	v_mfma_f32_32x32x16_bf16 v[66:81], v[182:185], v[98:101], v[66:81]
	v_exp_f32_e32 v183, v90
	v_exp_f32_e32 v184, v91
	v_add_f32_e32 v148, 0, v149
	v_add_f32_e32 v148, v150, v148
	v_exp_f32_e32 v185, v92
	v_mfma_f32_32x32x16_bf16 v[66:81], v[198:201], v[102:105], v[66:81]
	v_exp_f32_e32 v198, v93
	v_add_f32_e32 v148, v151, v148
	v_add_f32_e32 v148, v152, v148
	v_exp_f32_e32 v199, v94
	v_add_f32_e32 v148, v153, v148
	v_mfma_f32_32x32x16_bf16 v[66:81], v[202:205], v[106:109], v[66:81]
	v_exp_f32_e32 v200, v95
	v_add_f32_e32 v148, v164, v148
	v_add_f32_e32 v148, v181, v148
	v_exp_f32_e32 v201, v96
	v_add_f32_e32 v148, v225, v148
	v_mfma_f32_32x32x16_bf16 v[66:81], v[206:209], v[110:113], v[66:81]
	v_exp_f32_e32 v202, v97
	v_add_f32_e32 v148, v183, v148
	v_add_f32_e32 v148, v184, v148
	v_add_f32_e32 v148, v185, v148
	v_add_f32_e32 v148, v198, v148
	v_add_f32_e32 v148, v199, v148
	v_add_f32_e32 v148, v200, v148
	v_add_f32_e32 v148, v201, v148
	v_add_f32_e32 v148, v202, v148
	v_cmp_nge_f32_e32 vcc, s12, v148
	s_cbranch_vccz .LBB0_205
	v_max_f32_e32 v146, v83, v83
	v_max_f32_e32 v148, v82, v82
	v_max_f32_e32 v146, v148, v146
	v_max3_f32 v146, v146, v84, v85
	v_max3_f32 v146, v146, v86, v87
	v_max3_f32 v146, v146, v88, v89
	v_max3_f32 v146, v146, v90, v91
	v_max3_f32 v146, v146, v92, v93
	v_max3_f32 v146, v146, v94, v95
	v_max3_f32 v146, v146, v96, v97
	ds_bpermute_b32 v148, v159, v146
	s_waitcnt lgkmcnt(0)
	v_max3_f32 v148, v146, v148, 0
	v_sub_f32_e32 v82, v82, v148
	v_exp_f32_e32 v82, v82
	v_sub_f32_e32 v83, v83, v148
	v_exp_f32_e32 v83, v83
	v_sub_f32_e32 v84, v84, v148
	v_exp_f32_e32 v84, v84
	v_sub_f32_e32 v85, v85, v148
	v_exp_f32_e32 v85, v85
	v_sub_f32_e32 v86, v86, v148
	v_sub_f32_e32 v87, v87, v148
	v_add_f32_e32 v149, 0, v82
	v_exp_f32_e32 v86, v86
	v_exp_f32_e32 v87, v87
	v_add_f32_e32 v149, v83, v149
	v_sub_f32_e32 v88, v88, v148
	v_sub_f32_e32 v89, v89, v148
	v_add_f32_e32 v149, v84, v149
	v_exp_f32_e32 v88, v88
	v_exp_f32_e32 v89, v89
	v_add_f32_e32 v149, v85, v149
	v_add_f32_e32 v149, v86, v149
	v_cvt_pk_bf16_f32 v82, v82, v83
	v_cvt_pk_bf16_f32 v83, v84, v85
	v_cvt_pk_bf16_f32 v84, v86, v87
	v_sub_f32_e32 v86, v90, v148
	v_add_f32_e32 v149, v87, v149
	v_exp_f32_e32 v86, v86
	v_sub_f32_e32 v87, v91, v148
	v_add_f32_e32 v149, v88, v149
	v_cvt_pk_bf16_f32 v85, v88, v89
	v_exp_f32_e32 v87, v87
	v_sub_f32_e32 v88, v92, v148
	v_add_f32_e32 v149, v89, v149
	v_exp_f32_e32 v88, v88
	v_sub_f32_e32 v89, v93, v148
	v_exp_f32_e32 v89, v89
	v_sub_f32_e32 v91, v94, v148
	v_add_f32_e32 v90, v86, v149
	v_exp_f32_e32 v91, v91
	v_sub_f32_e32 v92, v95, v148
	v_add_f32_e32 v90, v87, v90
	v_exp_f32_e32 v92, v92
	v_sub_f32_e32 v93, v96, v148
	v_add_f32_e32 v90, v88, v90
	v_exp_f32_e32 v93, v93
	v_sub_f32_e32 v94, v97, v148
	v_exp_f32_e64 v146, -v148
	v_add_f32_e32 v90, v89, v90
	v_exp_f32_e32 v94, v94
	v_add_f32_e32 v90, v91, v90
	v_add_f32_e32 v90, v92, v90
	v_add_f32_e32 v0, v0, v148
	v_add_f32_e32 v90, v93, v90
	v_pk_mul_f32 v[64:65], v[64:65], v[146:147] op_sel_hi:[1,0]
	v_pk_mul_f32 v[62:63], v[62:63], v[146:147] op_sel_hi:[1,0]
	v_pk_mul_f32 v[60:61], v[60:61], v[146:147] op_sel_hi:[1,0]
	v_pk_mul_f32 v[58:59], v[58:59], v[146:147] op_sel_hi:[1,0]
	v_pk_mul_f32 v[56:57], v[56:57], v[146:147] op_sel_hi:[1,0]
	v_pk_mul_f32 v[54:55], v[54:55], v[146:147] op_sel_hi:[1,0]
	v_pk_mul_f32 v[52:53], v[52:53], v[146:147] op_sel_hi:[1,0]
	v_pk_mul_f32 v[50:51], v[50:51], v[146:147] op_sel_hi:[1,0]
	v_pk_mul_f32 v[48:49], v[48:49], v[146:147] op_sel_hi:[1,0]
	v_pk_mul_f32 v[46:47], v[46:47], v[146:147] op_sel_hi:[1,0]
	v_pk_mul_f32 v[44:45], v[44:45], v[146:147] op_sel_hi:[1,0]
	v_pk_mul_f32 v[42:43], v[42:43], v[146:147] op_sel_hi:[1,0]
	v_pk_mul_f32 v[40:41], v[40:41], v[146:147] op_sel_hi:[1,0]
	v_pk_mul_f32 v[38:39], v[38:39], v[146:147] op_sel_hi:[1,0]
	v_pk_mul_f32 v[36:37], v[36:37], v[146:147] op_sel_hi:[1,0]
	v_pk_mul_f32 v[34:35], v[34:35], v[146:147] op_sel_hi:[1,0]
	v_pk_mul_f32 v[32:33], v[32:33], v[146:147] op_sel_hi:[1,0]
	v_pk_mul_f32 v[30:31], v[30:31], v[146:147] op_sel_hi:[1,0]
	v_pk_mul_f32 v[28:29], v[28:29], v[146:147] op_sel_hi:[1,0]
	v_pk_mul_f32 v[26:27], v[26:27], v[146:147] op_sel_hi:[1,0]
	v_pk_mul_f32 v[24:25], v[24:25], v[146:147] op_sel_hi:[1,0]
	v_pk_mul_f32 v[22:23], v[22:23], v[146:147] op_sel_hi:[1,0]
	v_pk_mul_f32 v[20:21], v[20:21], v[146:147] op_sel_hi:[1,0]
	v_pk_mul_f32 v[18:19], v[18:19], v[146:147] op_sel_hi:[1,0]
	v_pk_mul_f32 v[16:17], v[16:17], v[146:147] op_sel_hi:[1,0]
	v_pk_mul_f32 v[14:15], v[14:15], v[146:147] op_sel_hi:[1,0]
	v_pk_mul_f32 v[12:13], v[12:13], v[146:147] op_sel_hi:[1,0]
	v_pk_mul_f32 v[10:11], v[10:11], v[146:147] op_sel_hi:[1,0]
	v_pk_mul_f32 v[8:9], v[8:9], v[146:147] op_sel_hi:[1,0]
	v_pk_mul_f32 v[6:7], v[6:7], v[146:147] op_sel_hi:[1,0]
	v_pk_mul_f32 v[4:5], v[4:5], v[146:147] op_sel_hi:[1,0]
	v_pk_mul_f32 v[2:3], v[2:3], v[146:147] op_sel_hi:[1,0]
	v_sub_f32_e32 v81, v81, v148
	v_sub_f32_e32 v80, v80, v148
	v_sub_f32_e32 v79, v79, v148
	v_sub_f32_e32 v78, v78, v148
	v_sub_f32_e32 v77, v77, v148
	v_sub_f32_e32 v76, v76, v148
	v_sub_f32_e32 v75, v75, v148
	v_sub_f32_e32 v74, v74, v148
	v_sub_f32_e32 v73, v73, v148
	v_sub_f32_e32 v72, v72, v148
	v_sub_f32_e32 v71, v71, v148
	v_sub_f32_e32 v70, v70, v148
	v_sub_f32_e32 v69, v69, v148
	v_sub_f32_e32 v68, v68, v148
	v_sub_f32_e32 v67, v67, v148
	v_sub_f32_e32 v66, v66, v148
	v_add_f32_e32 v148, v94, v90
	v_cvt_pk_bf16_f32 v86, v86, v87
	v_cvt_pk_bf16_f32 v87, v88, v89
	v_cvt_pk_bf16_f32 v88, v91, v92
	v_cvt_pk_bf16_f32 v89, v93, v94
	v_mul_f32_e32 v147, v147, v146
	v_xor_b32_e32 v146, 0x80000000, v0
	s_branch .LBB0_206
.LBB0_205:
	v_cvt_pk_bf16_f32 v82, v149, v150
	v_cvt_pk_bf16_f32 v83, v151, v152
	v_cvt_pk_bf16_f32 v84, v153, v164
	v_cvt_pk_bf16_f32 v85, v181, v225
	v_cvt_pk_bf16_f32 v86, v183, v184
	v_cvt_pk_bf16_f32 v87, v185, v198
	v_cvt_pk_bf16_f32 v88, v199, v200
	v_cvt_pk_bf16_f32 v89, v201, v202
.LBB0_206:
	v_mfma_f32_32x32x16_bf16 v[50:65], v[130:133], v[82:85], v[50:65]
	ds_read_b128 v[182:185], v169 offset:40960
	ds_read_b128 v[198:201], v170 offset:40960
	ds_read_b128 v[202:205], v171 offset:40960
	v_exp_f32_e32 v149, v66
	s_or_b32 s0, s0, 32
	s_cmp_lt_u32 s0, s84
	s_cselect_b64 s[44:45], -1, 0
	s_cmp_lg_u32 s0, s84
	v_mfma_f32_32x32x16_bf16 v[34:49], v[126:129], v[82:85], v[34:49]
	ds_read_b128 v[206:209], v172 offset:40960
	ds_read_b64_tr_b16 v[130:131], v173 offset:32768
	ds_read_b64_tr_b16 v[132:133], v174 offset:32768
	v_exp_f32_e32 v150, v67
	v_mfma_f32_32x32x16_bf16 v[18:33], v[122:125], v[82:85], v[18:33]
	ds_read_b64_tr_b16 v[126:127], v175 offset:32768
	ds_read_b64_tr_b16 v[128:129], v176 offset:32768
	ds_read_b64_tr_b16 v[122:123], v177 offset:32768
	v_exp_f32_e32 v151, v68
	v_mfma_f32_32x32x16_bf16 v[2:17], v[118:121], v[82:85], v[2:17]
	ds_read_b64_tr_b16 v[124:125], v178 offset:32768
	ds_read_b64_tr_b16 v[118:119], v179 offset:32768
	ds_read_b64_tr_b16 v[120:121], v180 offset:32768
	v_exp_f32_e32 v152, v69
	v_lshl_add_u64 v[250:251], v[248:249], 0, s[46:47]
	s_mov_b32 m0, s88
	s_nop 0
	global_load_lds_dwordx4 v[250:251], off
	v_or_b32_e32 v82, s0, v166
	v_sub_u32_e32 v82, v167, v82
	v_cvt_f32_i32_e32 v83, v82
	v_fma_f32 v96, -v158, |v83|, v146
	v_mfma_f32_32x32x16_bf16 v[50:65], v[114:117], v[86:89], v[50:65]
	ds_read_b64_tr_b16 v[114:115], v173 offset:36864
	ds_read_b64_tr_b16 v[116:117], v174 offset:36864
	v_exp_f32_e32 v153, v70
	v_mfma_f32_32x32x16_bf16 v[34:49], v[134:137], v[86:89], v[34:49]
	ds_read_b64_tr_b16 v[134:135], v175 offset:36864
	ds_read_b64_tr_b16 v[136:137], v176 offset:36864
	v_exp_f32_e32 v164, v71
	v_mfma_f32_32x32x16_bf16 v[18:33], v[138:141], v[86:89], v[18:33]
	ds_read_b64_tr_b16 v[138:139], v177 offset:36864
	ds_read_b64_tr_b16 v[140:141], v178 offset:36864
	v_exp_f32_e32 v181, v72
	v_mfma_f32_32x32x16_bf16 v[2:17], v[142:145], v[86:89], v[2:17]
	ds_read_b64_tr_b16 v[142:143], v179 offset:36864
	ds_read_b64_tr_b16 v[144:145], v180 offset:36864
	v_exp_f32_e32 v225, v73
	s_cbranch_scc1 .LBB0_208
	v_add_u32_e32 v83, -2, v82
	v_cvt_f32_i32_e32 v83, v83
	v_add_u32_e32 v84, -1, v82
	v_cvt_f32_i32_e32 v84, v84
	v_add_u32_e32 v86, -8, v82
	v_and_b32_e32 v85, 0x7fffffff, v83
	v_add_u32_e32 v83, -3, v82
	v_cvt_f32_i32_e32 v83, v83
	v_cvt_f32_i32_e32 v86, v86
	v_and_b32_e32 v84, 0x7fffffff, v84
	v_pk_fma_f32 v[210:211], v[162:163], v[84:85], v[146:147] op_sel_hi:[1,1,0]
	v_and_b32_e32 v84, 0x7fffffff, v83
	v_add_u32_e32 v83, -10, v82
	v_cvt_f32_i32_e32 v83, v83
	v_and_b32_e32 v85, 0x7fffffff, v86
	v_pk_fma_f32 v[212:213], v[162:163], v[84:85], v[146:147] op_sel_hi:[1,1,0]
	v_add_u32_e32 v84, -9, v82
	v_cvt_f32_i32_e32 v84, v84
	v_and_b32_e32 v85, 0x7fffffff, v83
	v_add_u32_e32 v83, -16, v82
	v_cvt_f32_i32_e32 v83, v83
	v_add_u32_e32 v86, -11, v82
	v_cvt_f32_i32_e32 v86, v86
	v_and_b32_e32 v84, 0x7fffffff, v84
	v_pk_fma_f32 v[214:215], v[162:163], v[84:85], v[146:147] op_sel_hi:[1,1,0]
	v_and_b32_e32 v85, 0x7fffffff, v83
	v_subrev_u32_e32 v83, 18, v82
	v_cvt_f32_i32_e32 v83, v83
	v_and_b32_e32 v84, 0x7fffffff, v86
	v_pk_fma_f32 v[216:217], v[162:163], v[84:85], v[146:147] op_sel_hi:[1,1,0]
	v_subrev_u32_e32 v84, 17, v82
	v_cvt_f32_i32_e32 v84, v84
	v_and_b32_e32 v85, 0x7fffffff, v83
	v_subrev_u32_e32 v83, 24, v82
	v_subrev_u32_e32 v86, 19, v82
	v_cvt_f32_i32_e32 v83, v83
	v_cvt_f32_i32_e32 v86, v86
	v_and_b32_e32 v84, 0x7fffffff, v84
	v_pk_fma_f32 v[218:219], v[162:163], v[84:85], v[146:147] op_sel_hi:[1,1,0]
	v_and_b32_e32 v85, 0x7fffffff, v83
	v_and_b32_e32 v84, 0x7fffffff, v86
	v_pk_fma_f32 v[220:221], v[162:163], v[84:85], v[146:147] op_sel_hi:[1,1,0]
	v_subrev_u32_e32 v83, 26, v82
	v_subrev_u32_e32 v84, 25, v82
	v_cvt_f32_i32_e32 v83, v83
	v_cvt_f32_i32_e32 v84, v84
	v_subrev_u32_e32 v82, 27, v82
	v_cvt_f32_i32_e32 v85, v82
	v_and_b32_e32 v83, 0x7fffffff, v83
	v_and_b32_e32 v82, 0x7fffffff, v84
	v_mov_b32_e32 v97, v210
	v_pk_fma_f32 v[222:223], v[162:163], v[82:83], v[146:147] op_sel_hi:[1,1,0]
	v_fma_f32 v224, -v158, |v85|, v146
	v_mov_b64_e32 v[82:83], v[96:97]
	v_mov_b64_e32 v[84:85], v[98:99]
	v_mov_b64_e32 v[86:87], v[100:101]
	v_mov_b64_e32 v[88:89], v[102:103]
	v_mov_b64_e32 v[90:91], v[104:105]
	v_mov_b64_e32 v[92:93], v[106:107]
	v_mov_b64_e32 v[94:95], v[108:109]
	v_mov_b64_e32 v[96:97], v[110:111]
	v_mov_b32_e32 v84, v211
	v_mov_b32_e32 v85, v212
	v_mov_b32_e32 v86, v213
	v_mov_b32_e32 v87, v214
	v_mov_b32_e32 v88, v215
	v_mov_b32_e32 v89, v216
	v_mov_b32_e32 v90, v217
	v_mov_b32_e32 v91, v218
	v_mov_b32_e32 v92, v219
	v_mov_b32_e32 v93, v220
	v_mov_b32_e32 v94, v221
	v_mov_b32_e32 v95, v222
	v_mov_b32_e32 v96, v223
	v_mov_b32_e32 v97, v224
	s_mov_b64 s[44:45], -1
	s_and_b64 vcc, exec, s[42:43]
	s_cbranch_vccnz .LBB0_209
	s_branch .LBB0_210

.LBB0_217:
	v_mfma_f32_32x32x16_bf16 v[50:65], v[130:133], v[66:69], v[50:65]
	ds_read_b128 v[182:185], v169 offset:49152
	ds_read_b128 v[198:201], v170 offset:49152
	ds_read_b128 v[202:205], v171 offset:49152
	v_exp_f32_e32 v149, v82
	s_cmp_lt_u32 s99, s84
	s_cselect_b64 s[48:49], -1, 0
	s_cmp_lg_u32 s99, s84
	v_mfma_f32_32x32x16_bf16 v[34:49], v[126:129], v[66:69], v[34:49]
	ds_read_b128 v[206:209], v172 offset:49152
	ds_read_b64_tr_b16 v[130:131], v173 offset:40960
	ds_read_b64_tr_b16 v[132:133], v174 offset:40960
	v_exp_f32_e32 v150, v83
	v_mfma_f32_32x32x16_bf16 v[18:33], v[122:125], v[66:69], v[18:33]
	ds_read_b64_tr_b16 v[126:127], v175 offset:40960
	ds_read_b64_tr_b16 v[128:129], v176 offset:40960
	ds_read_b64_tr_b16 v[122:123], v177 offset:40960
	v_exp_f32_e32 v151, v84
	v_mfma_f32_32x32x16_bf16 v[2:17], v[118:121], v[66:69], v[2:17]
	ds_read_b64_tr_b16 v[124:125], v178 offset:40960
	ds_read_b64_tr_b16 v[118:119], v179 offset:40960
	ds_read_b64_tr_b16 v[120:121], v180 offset:40960
	v_exp_f32_e32 v152, v85
	v_lshl_add_u64 v[250:251], v[248:249], 0, s[56:57]
	s_mov_b32 m0, s91
	s_nop 0
	global_load_lds_dwordx4 v[250:251], off
	v_or_b32_e32 v66, s99, v166
	v_sub_u32_e32 v66, v167, v66
	v_cvt_f32_i32_e32 v67, v66
	v_fma_f32 v80, -v158, |v67|, v146
	v_mfma_f32_32x32x16_bf16 v[50:65], v[114:117], v[70:73], v[50:65]
	ds_read_b64_tr_b16 v[114:115], v173 offset:45056
	ds_read_b64_tr_b16 v[116:117], v174 offset:45056
	v_exp_f32_e32 v153, v86
	v_mfma_f32_32x32x16_bf16 v[34:49], v[134:137], v[70:73], v[34:49]
	ds_read_b64_tr_b16 v[134:135], v175 offset:45056
	ds_read_b64_tr_b16 v[136:137], v176 offset:45056
	v_exp_f32_e32 v164, v87
	v_mfma_f32_32x32x16_bf16 v[18:33], v[138:141], v[70:73], v[18:33]
	ds_read_b64_tr_b16 v[138:139], v177 offset:45056
	ds_read_b64_tr_b16 v[140:141], v178 offset:45056
	v_exp_f32_e32 v181, v88
	v_mfma_f32_32x32x16_bf16 v[2:17], v[142:145], v[70:73], v[2:17]
	ds_read_b64_tr_b16 v[142:143], v179 offset:45056
	ds_read_b64_tr_b16 v[144:145], v180 offset:45056
	v_exp_f32_e32 v225, v89
	s_cbranch_scc1 .LBB0_219
	v_add_u32_e32 v67, -2, v66
	v_cvt_f32_i32_e32 v67, v67
	v_add_u32_e32 v68, -1, v66
	v_cvt_f32_i32_e32 v68, v68
	v_add_u32_e32 v70, -8, v66
	v_and_b32_e32 v69, 0x7fffffff, v67
	v_add_u32_e32 v67, -3, v66
	v_cvt_f32_i32_e32 v67, v67
	v_cvt_f32_i32_e32 v70, v70
	v_and_b32_e32 v68, 0x7fffffff, v68
	v_pk_fma_f32 v[210:211], v[162:163], v[68:69], v[146:147] op_sel_hi:[1,1,0]
	v_and_b32_e32 v68, 0x7fffffff, v67
	v_add_u32_e32 v67, -10, v66
	v_cvt_f32_i32_e32 v67, v67
	v_and_b32_e32 v69, 0x7fffffff, v70
	v_pk_fma_f32 v[212:213], v[162:163], v[68:69], v[146:147] op_sel_hi:[1,1,0]
	v_add_u32_e32 v68, -9, v66
	v_cvt_f32_i32_e32 v68, v68
	v_and_b32_e32 v69, 0x7fffffff, v67
	v_add_u32_e32 v67, -16, v66
	v_cvt_f32_i32_e32 v67, v67
	v_add_u32_e32 v70, -11, v66
	v_cvt_f32_i32_e32 v70, v70
	v_and_b32_e32 v68, 0x7fffffff, v68
	v_pk_fma_f32 v[214:215], v[162:163], v[68:69], v[146:147] op_sel_hi:[1,1,0]
	v_and_b32_e32 v69, 0x7fffffff, v67
	v_subrev_u32_e32 v67, 18, v66
	v_cvt_f32_i32_e32 v67, v67
	v_and_b32_e32 v68, 0x7fffffff, v70
	v_pk_fma_f32 v[216:217], v[162:163], v[68:69], v[146:147] op_sel_hi:[1,1,0]
	v_subrev_u32_e32 v68, 17, v66
	v_cvt_f32_i32_e32 v68, v68
	v_and_b32_e32 v69, 0x7fffffff, v67
	v_subrev_u32_e32 v67, 24, v66
	v_subrev_u32_e32 v70, 19, v66
	v_cvt_f32_i32_e32 v67, v67
	v_cvt_f32_i32_e32 v70, v70
	v_and_b32_e32 v68, 0x7fffffff, v68
	v_pk_fma_f32 v[218:219], v[162:163], v[68:69], v[146:147] op_sel_hi:[1,1,0]
	v_and_b32_e32 v69, 0x7fffffff, v67
	v_and_b32_e32 v68, 0x7fffffff, v70
	v_pk_fma_f32 v[220:221], v[162:163], v[68:69], v[146:147] op_sel_hi:[1,1,0]
	v_subrev_u32_e32 v67, 26, v66
	v_subrev_u32_e32 v68, 25, v66
	v_cvt_f32_i32_e32 v67, v67
	v_cvt_f32_i32_e32 v68, v68
	v_subrev_u32_e32 v66, 27, v66
	v_cvt_f32_i32_e32 v69, v66
	v_and_b32_e32 v67, 0x7fffffff, v67
	v_and_b32_e32 v66, 0x7fffffff, v68
	v_mov_b32_e32 v81, v210
	v_pk_fma_f32 v[222:223], v[162:163], v[66:67], v[146:147] op_sel_hi:[1,1,0]
	v_fma_f32 v224, -v158, |v69|, v146
	v_mov_b64_e32 v[66:67], v[80:81]
	v_mov_b64_e32 v[68:69], v[82:83]
	v_mov_b64_e32 v[70:71], v[84:85]
	v_mov_b64_e32 v[72:73], v[86:87]
	v_mov_b64_e32 v[74:75], v[88:89]
	v_mov_b64_e32 v[76:77], v[90:91]
	v_mov_b64_e32 v[78:79], v[92:93]
	v_mov_b64_e32 v[80:81], v[94:95]
	v_mov_b32_e32 v68, v211
	v_mov_b32_e32 v69, v212
	v_mov_b32_e32 v70, v213
	v_mov_b32_e32 v71, v214
	v_mov_b32_e32 v72, v215
	v_mov_b32_e32 v73, v216
	v_mov_b32_e32 v74, v217
	v_mov_b32_e32 v75, v218
	v_mov_b32_e32 v76, v219
	v_mov_b32_e32 v77, v220
	v_mov_b32_e32 v78, v221
	v_mov_b32_e32 v79, v222
	v_mov_b32_e32 v80, v223
	v_mov_b32_e32 v81, v224
	s_branch .LBB0_220

.LBB0_220:
	v_lshl_add_u64 v[250:251], v[248:249], 0, s[68:69]
	s_mov_b32 m0, s90
	s_nop 0
	global_load_lds_dwordx4 v[250:251], off
	v_add_f32_e32 v147, v148, v147
	s_waitcnt lgkmcnt(0)
	v_mfma_f32_32x32x16_bf16 v[66:81], v[182:185], v[98:101], v[66:81]
	v_exp_f32_e32 v183, v90
	v_exp_f32_e32 v184, v91
	v_add_f32_e32 v148, 0, v149
	v_add_f32_e32 v148, v150, v148
	v_exp_f32_e32 v185, v92
	v_mfma_f32_32x32x16_bf16 v[66:81], v[198:201], v[102:105], v[66:81]
	v_exp_f32_e32 v198, v93
	v_add_f32_e32 v148, v151, v148
	v_add_f32_e32 v148, v152, v148
	v_exp_f32_e32 v199, v94
	v_add_f32_e32 v148, v153, v148
	v_mfma_f32_32x32x16_bf16 v[66:81], v[202:205], v[106:109], v[66:81]
	v_exp_f32_e32 v200, v95
	v_add_f32_e32 v148, v164, v148
	v_add_f32_e32 v148, v181, v148
	v_exp_f32_e32 v201, v96
	v_add_f32_e32 v148, v225, v148
	v_mfma_f32_32x32x16_bf16 v[66:81], v[206:209], v[110:113], v[66:81]
	v_exp_f32_e32 v202, v97
	v_add_f32_e32 v148, v183, v148
	v_add_f32_e32 v148, v184, v148
	v_add_f32_e32 v148, v185, v148
	v_add_f32_e32 v148, v198, v148
	v_add_f32_e32 v148, v199, v148
	v_add_f32_e32 v148, v200, v148
	v_add_f32_e32 v148, v201, v148
	v_add_f32_e32 v148, v202, v148
	v_cmp_nge_f32_e32 vcc, s12, v148
	s_cbranch_vccz .LBB0_222
	v_max_f32_e32 v146, v83, v83
	v_max_f32_e32 v148, v82, v82
	v_max_f32_e32 v146, v148, v146
	v_max3_f32 v146, v146, v84, v85
	v_max3_f32 v146, v146, v86, v87
	v_max3_f32 v146, v146, v88, v89
	v_max3_f32 v146, v146, v90, v91
	v_max3_f32 v146, v146, v92, v93
	v_max3_f32 v146, v146, v94, v95
	v_max3_f32 v146, v146, v96, v97
	ds_bpermute_b32 v148, v159, v146
	s_waitcnt lgkmcnt(0)
	v_max3_f32 v148, v146, v148, 0
	v_sub_f32_e32 v82, v82, v148
	v_exp_f32_e32 v82, v82
	v_sub_f32_e32 v83, v83, v148
	v_exp_f32_e32 v83, v83
	v_sub_f32_e32 v84, v84, v148
	v_exp_f32_e32 v84, v84
	v_sub_f32_e32 v85, v85, v148
	v_exp_f32_e32 v85, v85
	v_sub_f32_e32 v86, v86, v148
	v_sub_f32_e32 v87, v87, v148
	v_add_f32_e32 v149, 0, v82
	v_exp_f32_e32 v86, v86
	v_exp_f32_e32 v87, v87
	v_add_f32_e32 v149, v83, v149
	v_sub_f32_e32 v88, v88, v148
	v_sub_f32_e32 v89, v89, v148
	v_add_f32_e32 v149, v84, v149
	v_exp_f32_e32 v88, v88
	v_exp_f32_e32 v89, v89
	v_add_f32_e32 v149, v85, v149
	v_add_f32_e32 v149, v86, v149
	v_cvt_pk_bf16_f32 v82, v82, v83
	v_cvt_pk_bf16_f32 v83, v84, v85
	v_cvt_pk_bf16_f32 v84, v86, v87
	v_sub_f32_e32 v86, v90, v148
	v_add_f32_e32 v149, v87, v149
	v_exp_f32_e32 v86, v86
	v_sub_f32_e32 v87, v91, v148
	v_add_f32_e32 v149, v88, v149
	v_cvt_pk_bf16_f32 v85, v88, v89
	v_exp_f32_e32 v87, v87
	v_sub_f32_e32 v88, v92, v148
	v_add_f32_e32 v149, v89, v149
	v_exp_f32_e32 v88, v88
	v_sub_f32_e32 v89, v93, v148
	v_exp_f32_e32 v89, v89
	v_sub_f32_e32 v91, v94, v148
	v_add_f32_e32 v90, v86, v149
	v_exp_f32_e32 v91, v91
	v_sub_f32_e32 v92, v95, v148
	v_add_f32_e32 v90, v87, v90
	v_exp_f32_e32 v92, v92
	v_sub_f32_e32 v93, v96, v148
	v_add_f32_e32 v90, v88, v90
	v_exp_f32_e32 v93, v93
	v_sub_f32_e32 v94, v97, v148
	v_exp_f32_e64 v146, -v148
	v_add_f32_e32 v90, v89, v90
	v_exp_f32_e32 v94, v94
	v_add_f32_e32 v90, v91, v90
	v_add_f32_e32 v90, v92, v90
	v_add_f32_e32 v0, v0, v148
	v_add_f32_e32 v90, v93, v90
	v_pk_mul_f32 v[64:65], v[64:65], v[146:147] op_sel_hi:[1,0]
	v_pk_mul_f32 v[62:63], v[62:63], v[146:147] op_sel_hi:[1,0]
	v_pk_mul_f32 v[60:61], v[60:61], v[146:147] op_sel_hi:[1,0]
	v_pk_mul_f32 v[58:59], v[58:59], v[146:147] op_sel_hi:[1,0]
	v_pk_mul_f32 v[56:57], v[56:57], v[146:147] op_sel_hi:[1,0]
	v_pk_mul_f32 v[54:55], v[54:55], v[146:147] op_sel_hi:[1,0]
	v_pk_mul_f32 v[52:53], v[52:53], v[146:147] op_sel_hi:[1,0]
	v_pk_mul_f32 v[50:51], v[50:51], v[146:147] op_sel_hi:[1,0]
	v_pk_mul_f32 v[48:49], v[48:49], v[146:147] op_sel_hi:[1,0]
	v_pk_mul_f32 v[46:47], v[46:47], v[146:147] op_sel_hi:[1,0]
	v_pk_mul_f32 v[44:45], v[44:45], v[146:147] op_sel_hi:[1,0]
	v_pk_mul_f32 v[42:43], v[42:43], v[146:147] op_sel_hi:[1,0]
	v_pk_mul_f32 v[40:41], v[40:41], v[146:147] op_sel_hi:[1,0]
	v_pk_mul_f32 v[38:39], v[38:39], v[146:147] op_sel_hi:[1,0]
	v_pk_mul_f32 v[36:37], v[36:37], v[146:147] op_sel_hi:[1,0]
	v_pk_mul_f32 v[34:35], v[34:35], v[146:147] op_sel_hi:[1,0]
	v_pk_mul_f32 v[32:33], v[32:33], v[146:147] op_sel_hi:[1,0]
	v_pk_mul_f32 v[30:31], v[30:31], v[146:147] op_sel_hi:[1,0]
	v_pk_mul_f32 v[28:29], v[28:29], v[146:147] op_sel_hi:[1,0]
	v_pk_mul_f32 v[26:27], v[26:27], v[146:147] op_sel_hi:[1,0]
	v_pk_mul_f32 v[24:25], v[24:25], v[146:147] op_sel_hi:[1,0]
	v_pk_mul_f32 v[22:23], v[22:23], v[146:147] op_sel_hi:[1,0]
	v_pk_mul_f32 v[20:21], v[20:21], v[146:147] op_sel_hi:[1,0]
	v_pk_mul_f32 v[18:19], v[18:19], v[146:147] op_sel_hi:[1,0]
	v_pk_mul_f32 v[16:17], v[16:17], v[146:147] op_sel_hi:[1,0]
	v_pk_mul_f32 v[14:15], v[14:15], v[146:147] op_sel_hi:[1,0]
	v_pk_mul_f32 v[12:13], v[12:13], v[146:147] op_sel_hi:[1,0]
	v_pk_mul_f32 v[10:11], v[10:11], v[146:147] op_sel_hi:[1,0]
	v_pk_mul_f32 v[8:9], v[8:9], v[146:147] op_sel_hi:[1,0]
	v_pk_mul_f32 v[6:7], v[6:7], v[146:147] op_sel_hi:[1,0]
	v_pk_mul_f32 v[4:5], v[4:5], v[146:147] op_sel_hi:[1,0]
	v_pk_mul_f32 v[2:3], v[2:3], v[146:147] op_sel_hi:[1,0]
	v_sub_f32_e32 v81, v81, v148
	v_sub_f32_e32 v80, v80, v148
	v_sub_f32_e32 v79, v79, v148
	v_sub_f32_e32 v78, v78, v148
	v_sub_f32_e32 v77, v77, v148
	v_sub_f32_e32 v76, v76, v148
	v_sub_f32_e32 v75, v75, v148
	v_sub_f32_e32 v74, v74, v148
	v_sub_f32_e32 v73, v73, v148
	v_sub_f32_e32 v72, v72, v148
	v_sub_f32_e32 v71, v71, v148
	v_sub_f32_e32 v70, v70, v148
	v_sub_f32_e32 v69, v69, v148
	v_sub_f32_e32 v68, v68, v148
	v_sub_f32_e32 v67, v67, v148
	v_sub_f32_e32 v66, v66, v148
	v_add_f32_e32 v148, v94, v90
	v_cvt_pk_bf16_f32 v86, v86, v87
	v_cvt_pk_bf16_f32 v87, v88, v89
	v_cvt_pk_bf16_f32 v88, v91, v92
	v_cvt_pk_bf16_f32 v89, v93, v94
	v_mul_f32_e32 v147, v147, v146
	v_xor_b32_e32 v146, 0x80000000, v0
	s_branch .LBB0_223

.LBB0_223:
	v_mfma_f32_32x32x16_bf16 v[50:65], v[130:133], v[82:85], v[50:65]
	ds_read_b128 v[182:185], v169 offset:57344
	ds_read_b128 v[198:201], v170 offset:57344
	ds_read_b128 v[202:205], v171 offset:57344
	v_exp_f32_e32 v149, v66
	s_or_b32 s0, s99, 32
	s_cmp_lt_u32 s0, s84
	s_cselect_b64 s[48:49], -1, 0
	s_cmp_lg_u32 s0, s84
	v_mfma_f32_32x32x16_bf16 v[34:49], v[126:129], v[82:85], v[34:49]
	ds_read_b128 v[206:209], v172 offset:57344
	ds_read_b64_tr_b16 v[130:131], v173 offset:49152
	ds_read_b64_tr_b16 v[132:133], v174 offset:49152
	v_exp_f32_e32 v150, v67
	v_mfma_f32_32x32x16_bf16 v[18:33], v[122:125], v[82:85], v[18:33]
	ds_read_b64_tr_b16 v[126:127], v175 offset:49152
	ds_read_b64_tr_b16 v[128:129], v176 offset:49152
	ds_read_b64_tr_b16 v[122:123], v177 offset:49152
	v_exp_f32_e32 v151, v68
	v_mfma_f32_32x32x16_bf16 v[2:17], v[118:121], v[82:85], v[2:17]
	ds_read_b64_tr_b16 v[124:125], v178 offset:49152
	ds_read_b64_tr_b16 v[118:119], v179 offset:49152
	ds_read_b64_tr_b16 v[120:121], v180 offset:49152
	v_exp_f32_e32 v152, v69
	v_lshl_add_u64 v[250:251], v[248:249], 0, s[46:47]
	s_mov_b32 m0, s92
	s_nop 0
	global_load_lds_dwordx4 v[250:251], off
	v_or_b32_e32 v82, s0, v166
	v_sub_u32_e32 v82, v167, v82
	v_cvt_f32_i32_e32 v83, v82
	v_fma_f32 v96, -v158, |v83|, v146
	v_mfma_f32_32x32x16_bf16 v[50:65], v[114:117], v[86:89], v[50:65]
	ds_read_b64_tr_b16 v[114:115], v173 offset:53248
	ds_read_b64_tr_b16 v[116:117], v174 offset:53248
	v_exp_f32_e32 v153, v70
	v_mfma_f32_32x32x16_bf16 v[34:49], v[134:137], v[86:89], v[34:49]
	ds_read_b64_tr_b16 v[134:135], v175 offset:53248
	ds_read_b64_tr_b16 v[136:137], v176 offset:53248
	v_exp_f32_e32 v164, v71
	v_mfma_f32_32x32x16_bf16 v[18:33], v[138:141], v[86:89], v[18:33]
	ds_read_b64_tr_b16 v[138:139], v177 offset:53248
	ds_read_b64_tr_b16 v[140:141], v178 offset:53248
	v_exp_f32_e32 v181, v72
	v_mfma_f32_32x32x16_bf16 v[2:17], v[142:145], v[86:89], v[2:17]
	ds_read_b64_tr_b16 v[142:143], v179 offset:53248
	ds_read_b64_tr_b16 v[144:145], v180 offset:53248
	v_exp_f32_e32 v225, v73
	s_cbranch_scc1 .LBB0_225
	v_add_u32_e32 v83, -2, v82
	v_cvt_f32_i32_e32 v83, v83
	v_add_u32_e32 v84, -1, v82
	v_cvt_f32_i32_e32 v84, v84
	v_add_u32_e32 v86, -8, v82
	v_and_b32_e32 v85, 0x7fffffff, v83
	v_add_u32_e32 v83, -3, v82
	v_cvt_f32_i32_e32 v83, v83
	v_cvt_f32_i32_e32 v86, v86
	v_and_b32_e32 v84, 0x7fffffff, v84
	v_pk_fma_f32 v[210:211], v[162:163], v[84:85], v[146:147] op_sel_hi:[1,1,0]
	v_and_b32_e32 v84, 0x7fffffff, v83
	v_add_u32_e32 v83, -10, v82
	v_cvt_f32_i32_e32 v83, v83
	v_and_b32_e32 v85, 0x7fffffff, v86
	v_pk_fma_f32 v[212:213], v[162:163], v[84:85], v[146:147] op_sel_hi:[1,1,0]
	v_add_u32_e32 v84, -9, v82
	v_cvt_f32_i32_e32 v84, v84
	v_and_b32_e32 v85, 0x7fffffff, v83
	v_add_u32_e32 v83, -16, v82
	v_cvt_f32_i32_e32 v83, v83
	v_add_u32_e32 v86, -11, v82
	v_cvt_f32_i32_e32 v86, v86
	v_and_b32_e32 v84, 0x7fffffff, v84
	v_pk_fma_f32 v[214:215], v[162:163], v[84:85], v[146:147] op_sel_hi:[1,1,0]
	v_and_b32_e32 v85, 0x7fffffff, v83
	v_subrev_u32_e32 v83, 18, v82
	v_cvt_f32_i32_e32 v83, v83
	v_and_b32_e32 v84, 0x7fffffff, v86
	v_pk_fma_f32 v[216:217], v[162:163], v[84:85], v[146:147] op_sel_hi:[1,1,0]
	v_subrev_u32_e32 v84, 17, v82
	v_cvt_f32_i32_e32 v84, v84
	v_and_b32_e32 v85, 0x7fffffff, v83
	v_subrev_u32_e32 v83, 24, v82
	v_subrev_u32_e32 v86, 19, v82
	v_cvt_f32_i32_e32 v83, v83
	v_cvt_f32_i32_e32 v86, v86
	v_and_b32_e32 v84, 0x7fffffff, v84
	v_pk_fma_f32 v[218:219], v[162:163], v[84:85], v[146:147] op_sel_hi:[1,1,0]
	v_and_b32_e32 v85, 0x7fffffff, v83
	v_and_b32_e32 v84, 0x7fffffff, v86
	v_pk_fma_f32 v[220:221], v[162:163], v[84:85], v[146:147] op_sel_hi:[1,1,0]
	v_subrev_u32_e32 v83, 26, v82
	v_subrev_u32_e32 v84, 25, v82
	v_cvt_f32_i32_e32 v83, v83
	v_cvt_f32_i32_e32 v84, v84
	v_subrev_u32_e32 v82, 27, v82
	v_cvt_f32_i32_e32 v85, v82
	v_and_b32_e32 v83, 0x7fffffff, v83
	v_and_b32_e32 v82, 0x7fffffff, v84
	v_mov_b32_e32 v97, v210
	v_pk_fma_f32 v[222:223], v[162:163], v[82:83], v[146:147] op_sel_hi:[1,1,0]
	v_fma_f32 v224, -v158, |v85|, v146
	v_mov_b64_e32 v[82:83], v[96:97]
	v_mov_b64_e32 v[84:85], v[98:99]
	v_mov_b64_e32 v[86:87], v[100:101]
	v_mov_b64_e32 v[88:89], v[102:103]
	v_mov_b64_e32 v[90:91], v[104:105]
	v_mov_b64_e32 v[92:93], v[106:107]
	v_mov_b64_e32 v[94:95], v[108:109]
	v_mov_b64_e32 v[96:97], v[110:111]
	v_mov_b32_e32 v84, v211
	v_mov_b32_e32 v85, v212
	v_mov_b32_e32 v86, v213
	v_mov_b32_e32 v87, v214
	v_mov_b32_e32 v88, v215
	v_mov_b32_e32 v89, v216
	v_mov_b32_e32 v90, v217
	v_mov_b32_e32 v91, v218
	v_mov_b32_e32 v92, v219
	v_mov_b32_e32 v93, v220
	v_mov_b32_e32 v94, v221
	v_mov_b32_e32 v95, v222
	v_mov_b32_e32 v96, v223
	v_mov_b32_e32 v97, v224
	s_mov_b64 s[48:49], -1
	s_and_b64 vcc, exec, s[44:45]
	s_cbranch_vccnz .LBB0_226
	s_branch .LBB0_227

.LBB0_234:
	v_mfma_f32_32x32x16_bf16 v[50:65], v[130:133], v[66:69], v[50:65]
	ds_read_b128 v[182:185], v169
	ds_read_b128 v[198:201], v170
	ds_read_b128 v[202:205], v171
	v_exp_f32_e32 v149, v82
	s_add_i32 s0, s97, 0xffffff80
	s_and_b32 s0, s0, 0xf80
	s_cmp_lt_u32 s0, s84
	s_cselect_b64 s[44:45], -1, 0
	s_cmp_lg_u32 s0, s84
	v_mfma_f32_32x32x16_bf16 v[34:49], v[126:129], v[66:69], v[34:49]
	ds_read_b128 v[206:209], v172
	ds_read_b64_tr_b16 v[130:131], v173 offset:57344
	ds_read_b64_tr_b16 v[132:133], v174 offset:57344
	v_exp_f32_e32 v150, v83
	v_mfma_f32_32x32x16_bf16 v[18:33], v[122:125], v[66:69], v[18:33]
	ds_read_b64_tr_b16 v[126:127], v175 offset:57344
	ds_read_b64_tr_b16 v[128:129], v176 offset:57344
	ds_read_b64_tr_b16 v[122:123], v177 offset:57344
	v_exp_f32_e32 v151, v84
	v_mfma_f32_32x32x16_bf16 v[2:17], v[118:121], v[66:69], v[2:17]
	ds_read_b64_tr_b16 v[124:125], v178 offset:57344
	ds_read_b64_tr_b16 v[118:119], v179 offset:57344
	ds_read_b64_tr_b16 v[120:121], v180 offset:57344
	v_exp_f32_e32 v152, v85
	v_lshl_add_u64 v[250:251], v[248:249], 0, s[56:57]
	s_mov_b32 m0, s95
	s_nop 0
	global_load_lds_dwordx4 v[250:251], off
	v_or_b32_e32 v66, s0, v166
	v_sub_u32_e32 v66, v167, v66
	v_cvt_f32_i32_e32 v67, v66
	v_fma_f32 v80, -v158, |v67|, v146
	v_mfma_f32_32x32x16_bf16 v[50:65], v[114:117], v[70:73], v[50:65]
	ds_read_b64_tr_b16 v[114:115], v173 offset:61440
	ds_read_b64_tr_b16 v[116:117], v174 offset:61440
	v_exp_f32_e32 v153, v86
	v_mfma_f32_32x32x16_bf16 v[34:49], v[134:137], v[70:73], v[34:49]
	ds_read_b64_tr_b16 v[134:135], v175 offset:61440
	ds_read_b64_tr_b16 v[136:137], v176 offset:61440
	v_exp_f32_e32 v164, v87
	v_mfma_f32_32x32x16_bf16 v[18:33], v[138:141], v[70:73], v[18:33]
	ds_read_b64_tr_b16 v[138:139], v177 offset:61440
	ds_read_b64_tr_b16 v[140:141], v178 offset:61440
	v_exp_f32_e32 v181, v88
	v_mfma_f32_32x32x16_bf16 v[2:17], v[142:145], v[70:73], v[2:17]
	ds_read_b64_tr_b16 v[142:143], v179 offset:61440
	ds_read_b64_tr_b16 v[144:145], v180 offset:61440
	v_exp_f32_e32 v225, v89
	s_cbranch_scc1 .LBB0_236
	v_add_u32_e32 v67, -2, v66
	v_cvt_f32_i32_e32 v67, v67
	v_add_u32_e32 v68, -1, v66
	v_cvt_f32_i32_e32 v68, v68
	v_add_u32_e32 v70, -8, v66
	v_and_b32_e32 v69, 0x7fffffff, v67
	v_add_u32_e32 v67, -3, v66
	v_cvt_f32_i32_e32 v67, v67
	v_cvt_f32_i32_e32 v70, v70
	v_and_b32_e32 v68, 0x7fffffff, v68
	v_pk_fma_f32 v[210:211], v[162:163], v[68:69], v[146:147] op_sel_hi:[1,1,0]
	v_and_b32_e32 v68, 0x7fffffff, v67
	v_add_u32_e32 v67, -10, v66
	v_cvt_f32_i32_e32 v67, v67
	v_and_b32_e32 v69, 0x7fffffff, v70
	v_pk_fma_f32 v[212:213], v[162:163], v[68:69], v[146:147] op_sel_hi:[1,1,0]
	v_add_u32_e32 v68, -9, v66
	v_cvt_f32_i32_e32 v68, v68
	v_and_b32_e32 v69, 0x7fffffff, v67
	v_add_u32_e32 v67, -16, v66
	v_cvt_f32_i32_e32 v67, v67
	v_add_u32_e32 v70, -11, v66
	v_cvt_f32_i32_e32 v70, v70
	v_and_b32_e32 v68, 0x7fffffff, v68
	v_pk_fma_f32 v[214:215], v[162:163], v[68:69], v[146:147] op_sel_hi:[1,1,0]
	v_and_b32_e32 v69, 0x7fffffff, v67
	v_subrev_u32_e32 v67, 18, v66
	v_cvt_f32_i32_e32 v67, v67
	v_and_b32_e32 v68, 0x7fffffff, v70
	v_pk_fma_f32 v[216:217], v[162:163], v[68:69], v[146:147] op_sel_hi:[1,1,0]
	v_subrev_u32_e32 v68, 17, v66
	v_cvt_f32_i32_e32 v68, v68
	v_and_b32_e32 v69, 0x7fffffff, v67
	v_subrev_u32_e32 v67, 24, v66
	v_subrev_u32_e32 v70, 19, v66
	v_cvt_f32_i32_e32 v67, v67
	v_cvt_f32_i32_e32 v70, v70
	v_and_b32_e32 v68, 0x7fffffff, v68
	v_pk_fma_f32 v[218:219], v[162:163], v[68:69], v[146:147] op_sel_hi:[1,1,0]
	v_and_b32_e32 v69, 0x7fffffff, v67
	v_and_b32_e32 v68, 0x7fffffff, v70
	v_pk_fma_f32 v[220:221], v[162:163], v[68:69], v[146:147] op_sel_hi:[1,1,0]
	v_subrev_u32_e32 v67, 26, v66
	v_subrev_u32_e32 v68, 25, v66
	v_cvt_f32_i32_e32 v67, v67
	v_cvt_f32_i32_e32 v68, v68
	v_subrev_u32_e32 v66, 27, v66
	v_cvt_f32_i32_e32 v69, v66
	v_and_b32_e32 v67, 0x7fffffff, v67
	v_and_b32_e32 v66, 0x7fffffff, v68
	v_mov_b32_e32 v81, v210
	v_pk_fma_f32 v[222:223], v[162:163], v[66:67], v[146:147] op_sel_hi:[1,1,0]
	v_fma_f32 v224, -v158, |v69|, v146
	v_mov_b64_e32 v[66:67], v[80:81]
	v_mov_b64_e32 v[68:69], v[82:83]
	v_mov_b64_e32 v[70:71], v[84:85]
	v_mov_b64_e32 v[72:73], v[86:87]
	v_mov_b64_e32 v[74:75], v[88:89]
	v_mov_b64_e32 v[76:77], v[90:91]
	v_mov_b64_e32 v[78:79], v[92:93]
	v_mov_b64_e32 v[80:81], v[94:95]
	v_mov_b32_e32 v68, v211
	v_mov_b32_e32 v69, v212
	v_mov_b32_e32 v70, v213
	v_mov_b32_e32 v71, v214
	v_mov_b32_e32 v72, v215
	v_mov_b32_e32 v73, v216
	v_mov_b32_e32 v74, v217
	v_mov_b32_e32 v75, v218
	v_mov_b32_e32 v76, v219
	v_mov_b32_e32 v77, v220
	v_mov_b32_e32 v78, v221
	v_mov_b32_e32 v79, v222
	v_mov_b32_e32 v80, v223
	v_mov_b32_e32 v81, v224
	s_branch .LBB0_237

.LBB0_237:
	v_lshl_add_u64 v[250:251], v[248:249], 0, s[68:69]
	s_mov_b32 m0, s94
	s_nop 0
	global_load_lds_dwordx4 v[250:251], off
	v_add_f32_e32 v147, v148, v147
	s_waitcnt lgkmcnt(0)
	v_mfma_f32_32x32x16_bf16 v[66:81], v[182:185], v[98:101], v[66:81]
	v_exp_f32_e32 v183, v90
	v_exp_f32_e32 v184, v91
	v_add_f32_e32 v148, 0, v149
	v_add_f32_e32 v148, v150, v148
	v_exp_f32_e32 v185, v92
	v_mfma_f32_32x32x16_bf16 v[66:81], v[198:201], v[102:105], v[66:81]
	v_exp_f32_e32 v198, v93
	v_add_f32_e32 v148, v151, v148
	v_add_f32_e32 v148, v152, v148
	v_exp_f32_e32 v199, v94
	v_add_f32_e32 v148, v153, v148
	v_mfma_f32_32x32x16_bf16 v[66:81], v[202:205], v[106:109], v[66:81]
	v_exp_f32_e32 v200, v95
	v_add_f32_e32 v148, v164, v148
	v_add_f32_e32 v148, v181, v148
	v_exp_f32_e32 v201, v96
	v_add_f32_e32 v148, v225, v148
	v_mfma_f32_32x32x16_bf16 v[66:81], v[206:209], v[110:113], v[66:81]
	v_exp_f32_e32 v202, v97
	v_add_f32_e32 v148, v183, v148
	v_add_f32_e32 v148, v184, v148
	v_add_f32_e32 v148, v185, v148
	v_add_f32_e32 v148, v198, v148
	v_add_f32_e32 v148, v199, v148
	v_add_f32_e32 v148, v200, v148
	v_add_f32_e32 v148, v201, v148
	v_add_f32_e32 v148, v202, v148
	v_cmp_nge_f32_e32 vcc, s12, v148
	s_cbranch_vccz .LBB0_239
	v_max_f32_e32 v146, v83, v83
	v_max_f32_e32 v148, v82, v82
	v_max_f32_e32 v146, v148, v146
	v_max3_f32 v146, v146, v84, v85
	v_max3_f32 v146, v146, v86, v87
	v_max3_f32 v146, v146, v88, v89
	v_max3_f32 v146, v146, v90, v91
	v_max3_f32 v146, v146, v92, v93
	v_max3_f32 v146, v146, v94, v95
	v_max3_f32 v146, v146, v96, v97
	ds_bpermute_b32 v148, v159, v146
	s_waitcnt lgkmcnt(0)
	v_max3_f32 v148, v146, v148, 0
	v_sub_f32_e32 v82, v82, v148
	v_exp_f32_e32 v82, v82
	v_sub_f32_e32 v83, v83, v148
	v_exp_f32_e32 v83, v83
	v_sub_f32_e32 v84, v84, v148
	v_exp_f32_e32 v84, v84
	v_sub_f32_e32 v85, v85, v148
	v_exp_f32_e32 v85, v85
	v_sub_f32_e32 v86, v86, v148
	v_sub_f32_e32 v87, v87, v148
	v_add_f32_e32 v149, 0, v82
	v_exp_f32_e32 v86, v86
	v_exp_f32_e32 v87, v87
	v_add_f32_e32 v149, v83, v149
	v_sub_f32_e32 v88, v88, v148
	v_sub_f32_e32 v89, v89, v148
	v_add_f32_e32 v149, v84, v149
	v_exp_f32_e32 v88, v88
	v_exp_f32_e32 v89, v89
	v_add_f32_e32 v149, v85, v149
	v_add_f32_e32 v149, v86, v149
	v_cvt_pk_bf16_f32 v82, v82, v83
	v_cvt_pk_bf16_f32 v83, v84, v85
	v_cvt_pk_bf16_f32 v84, v86, v87
	v_sub_f32_e32 v86, v90, v148
	v_add_f32_e32 v149, v87, v149
	v_exp_f32_e32 v86, v86
	v_sub_f32_e32 v87, v91, v148
	v_add_f32_e32 v149, v88, v149
	v_cvt_pk_bf16_f32 v85, v88, v89
	v_exp_f32_e32 v87, v87
	v_sub_f32_e32 v88, v92, v148
	v_add_f32_e32 v149, v89, v149
	v_exp_f32_e32 v88, v88
	v_sub_f32_e32 v89, v93, v148
	v_exp_f32_e32 v89, v89
	v_sub_f32_e32 v91, v94, v148
	v_add_f32_e32 v90, v86, v149
	v_exp_f32_e32 v91, v91
	v_sub_f32_e32 v92, v95, v148
	v_add_f32_e32 v90, v87, v90
	v_exp_f32_e32 v92, v92
	v_sub_f32_e32 v93, v96, v148
	v_add_f32_e32 v90, v88, v90
	v_exp_f32_e32 v93, v93
	v_sub_f32_e32 v94, v97, v148
	v_exp_f32_e64 v146, -v148
	v_add_f32_e32 v90, v89, v90
	v_exp_f32_e32 v94, v94
	v_add_f32_e32 v90, v91, v90
	v_add_f32_e32 v90, v92, v90
	v_add_f32_e32 v0, v0, v148
	v_add_f32_e32 v90, v93, v90
	v_pk_mul_f32 v[64:65], v[64:65], v[146:147] op_sel_hi:[1,0]
	v_pk_mul_f32 v[62:63], v[62:63], v[146:147] op_sel_hi:[1,0]
	v_pk_mul_f32 v[60:61], v[60:61], v[146:147] op_sel_hi:[1,0]
	v_pk_mul_f32 v[58:59], v[58:59], v[146:147] op_sel_hi:[1,0]
	v_pk_mul_f32 v[56:57], v[56:57], v[146:147] op_sel_hi:[1,0]
	v_pk_mul_f32 v[54:55], v[54:55], v[146:147] op_sel_hi:[1,0]
	v_pk_mul_f32 v[52:53], v[52:53], v[146:147] op_sel_hi:[1,0]
	v_pk_mul_f32 v[50:51], v[50:51], v[146:147] op_sel_hi:[1,0]
	v_pk_mul_f32 v[48:49], v[48:49], v[146:147] op_sel_hi:[1,0]
	v_pk_mul_f32 v[46:47], v[46:47], v[146:147] op_sel_hi:[1,0]
	v_pk_mul_f32 v[44:45], v[44:45], v[146:147] op_sel_hi:[1,0]
	v_pk_mul_f32 v[42:43], v[42:43], v[146:147] op_sel_hi:[1,0]
	v_pk_mul_f32 v[40:41], v[40:41], v[146:147] op_sel_hi:[1,0]
	v_pk_mul_f32 v[38:39], v[38:39], v[146:147] op_sel_hi:[1,0]
	v_pk_mul_f32 v[36:37], v[36:37], v[146:147] op_sel_hi:[1,0]
	v_pk_mul_f32 v[34:35], v[34:35], v[146:147] op_sel_hi:[1,0]
	v_pk_mul_f32 v[32:33], v[32:33], v[146:147] op_sel_hi:[1,0]
	v_pk_mul_f32 v[30:31], v[30:31], v[146:147] op_sel_hi:[1,0]
	v_pk_mul_f32 v[28:29], v[28:29], v[146:147] op_sel_hi:[1,0]
	v_pk_mul_f32 v[26:27], v[26:27], v[146:147] op_sel_hi:[1,0]
	v_pk_mul_f32 v[24:25], v[24:25], v[146:147] op_sel_hi:[1,0]
	v_pk_mul_f32 v[22:23], v[22:23], v[146:147] op_sel_hi:[1,0]
	v_pk_mul_f32 v[20:21], v[20:21], v[146:147] op_sel_hi:[1,0]
	v_pk_mul_f32 v[18:19], v[18:19], v[146:147] op_sel_hi:[1,0]
	v_pk_mul_f32 v[16:17], v[16:17], v[146:147] op_sel_hi:[1,0]
	v_pk_mul_f32 v[14:15], v[14:15], v[146:147] op_sel_hi:[1,0]
	v_pk_mul_f32 v[12:13], v[12:13], v[146:147] op_sel_hi:[1,0]
	v_pk_mul_f32 v[10:11], v[10:11], v[146:147] op_sel_hi:[1,0]
	v_pk_mul_f32 v[8:9], v[8:9], v[146:147] op_sel_hi:[1,0]
	v_pk_mul_f32 v[6:7], v[6:7], v[146:147] op_sel_hi:[1,0]
	v_pk_mul_f32 v[4:5], v[4:5], v[146:147] op_sel_hi:[1,0]
	v_pk_mul_f32 v[2:3], v[2:3], v[146:147] op_sel_hi:[1,0]
	v_sub_f32_e32 v81, v81, v148
	v_sub_f32_e32 v80, v80, v148
	v_sub_f32_e32 v79, v79, v148
	v_sub_f32_e32 v78, v78, v148
	v_sub_f32_e32 v77, v77, v148
	v_sub_f32_e32 v76, v76, v148
	v_sub_f32_e32 v75, v75, v148
	v_sub_f32_e32 v74, v74, v148
	v_sub_f32_e32 v73, v73, v148
	v_sub_f32_e32 v72, v72, v148
	v_sub_f32_e32 v71, v71, v148
	v_sub_f32_e32 v70, v70, v148
	v_sub_f32_e32 v69, v69, v148
	v_sub_f32_e32 v68, v68, v148
	v_sub_f32_e32 v67, v67, v148
	v_sub_f32_e32 v66, v66, v148
	v_add_f32_e32 v148, v94, v90
	v_cvt_pk_bf16_f32 v86, v86, v87
	v_cvt_pk_bf16_f32 v87, v88, v89
	v_cvt_pk_bf16_f32 v88, v91, v92
	v_cvt_pk_bf16_f32 v89, v93, v94
	v_mul_f32_e32 v147, v147, v146
	v_xor_b32_e32 v146, 0x80000000, v0
	s_branch .LBB0_240
